# attention phase B: second half-step's staging also retires the loads issued just before it, on top of the last-step trimming
# baseline (speedup 1.0000x reference)
.LBB0_555:
	s_add_i32 s67, s67, 1
	s_and_b64 s[0:1], s[38:39], exec
	s_cselect_b32 s14, s66, s67
	s_and_b64 s[0:1], s[18:19], exec
	s_cselect_b32 s78, s67, s14
	s_xor_b64 s[0:1], s[18:19], -1
	v_cndmask_b32_e64 v2, 0, 1, s[0:1]
	s_waitcnt vmcnt(14)
	ds_write_b128 v219, v[48:51]
	s_waitcnt vmcnt(12)
	ds_write_b128 v219, v[60:63] offset:1152
	s_cmp_eq_u64 s[18:19], 0
	s_addc_u32 s99, s77, 0
	s_cmp_lg_u32 s99, 2
	s_cbranch_scc1 .Lat_full2
	s_cmp_lg_u32 s78, 2
	s_cbranch_scc1 .Lat_full2
	ds_write_b128 v220, v[56:59] offset:9216
	ds_write_b128 v220, v[72:75] offset:10240
	s_waitcnt vmcnt(0)
	s_setprio 1
	s_branch .Lat_done2
.Lat_full2:
	s_waitcnt vmcnt(10)
	ds_write_b128 v219, v[80:83] offset:2304
	s_waitcnt vmcnt(8)
	ds_write_b128 v219, v[92:95] offset:3456
	s_waitcnt vmcnt(6)
	ds_write_b128 v219, v[100:103] offset:4608
	s_waitcnt vmcnt(4)
	ds_write_b128 v219, v[108:111] offset:5760
	s_waitcnt vmcnt(2)
	ds_write_b128 v219, v[116:119] offset:6912
	s_waitcnt vmcnt(0)
	ds_write_b128 v219, v[124:127] offset:8064
	ds_write_b128 v220, v[56:59] offset:9216
	ds_write_b128 v220, v[72:75] offset:10240
	ds_write_b128 v220, v[84:87] offset:11264
	ds_write_b128 v220, v[96:99] offset:12288
	ds_write_b128 v220, v[104:107] offset:13312
	ds_write_b128 v220, v[112:115] offset:14336
	ds_write_b128 v220, v[120:123] offset:15360
	s_setprio 1
	ds_write_b128 v220, v[128:131] offset:16384
